# ProbOut fused epilogue rewritten by hand: x/gate loads batched 4 blocks deep with counted vmcnt, row sum-of-squares reduced once for 8 blocks, 8 returning atomics then one wait, post-exchange rowsq/fi
# speedup vs baseline: 1.0310x; 1.0310x over previous
.LBB0_733:
	v_readlane_b32 s16, v241, 0
	v_readlane_b32 s17, v241, 1
	s_waitcnt lgkmcnt(0)
	global_load_dwordx4 v[140:143], v[254:255], off
	global_load_dwordx4 v[136:139], v[254:255], off offset:64
	global_load_dwordx4 v[132:135], v[254:255], off offset:512
	global_load_dwordx4 v[128:131], v[254:255], off offset:576
	global_load_dword v246, v[168:169], off sc1
	global_load_dword v247, v[168:169], off offset:64 sc1
	global_load_dword v248, v[168:169], off offset:128 sc1
	global_load_dword v249, v[168:169], off offset:192 sc1
	global_load_dword v250, v[168:169], off offset:512 sc1
	global_load_dword v251, v[168:169], off offset:576 sc1
	global_load_dword v252, v[168:169], off offset:640 sc1
	global_load_dword v253, v[168:169], off offset:704 sc1
	v_lshl_add_u64 v[170:171], v[186:187], 0, s[16:17]
	s_waitcnt vmcnt(0)
	v_fmamk_f32 v174, v246, 0x3a800000, v195
	v_mul_f32_e32 v175, 0x4b800000, v174
	v_cmp_gt_f32_e32 vcc, s44, v174
	s_nop 1
	v_cndmask_b32_e32 v174, v174, v175, vcc
	v_rsq_f32_e32 v144, v174
	s_nop 0
	v_mul_f32_e32 v175, 0x45800000, v144
	v_cndmask_b32_e32 v144, v144, v175, vcc
	v_pk_mul_f32 v[124:125], v[124:125], v[144:145] op_sel_hi:[1,0]
	v_pk_mul_f32 v[126:127], v[126:127], v[144:145] op_sel_hi:[1,0]
	v_pk_mul_f32 v[120:121], v[120:121], v[144:145] op_sel_hi:[1,0]
	v_pk_mul_f32 v[122:123], v[122:123], v[144:145] op_sel_hi:[1,0]
	v_pk_mul_f32 v[116:117], v[116:117], v[144:145] op_sel_hi:[1,0]
	v_pk_mul_f32 v[118:119], v[118:119], v[144:145] op_sel_hi:[1,0]
	v_pk_mul_f32 v[112:113], v[112:113], v[144:145] op_sel_hi:[1,0]
	v_pk_mul_f32 v[114:115], v[114:115], v[144:145] op_sel_hi:[1,0]
	v_pk_mul_f32 v[124:125], v[140:141], v[124:125]
	v_pk_mul_f32 v[126:127], v[142:143], v[126:127]
	v_pk_mul_f32 v[120:121], v[136:137], v[120:121]
	v_pk_mul_f32 v[122:123], v[138:139], v[122:123]
	v_pk_mul_f32 v[116:117], v[132:133], v[116:117]
	v_pk_mul_f32 v[118:119], v[134:135], v[118:119]
	v_pk_mul_f32 v[112:113], v[128:129], v[112:113]
	v_pk_mul_f32 v[114:115], v[130:131], v[114:115]
	global_store_dwordx4 v[170:171], v[124:127], off
	global_store_dwordx4 v[170:171], v[120:123], off offset:64
	global_store_dwordx4 v[170:171], v[116:119], off offset:512
	global_store_dwordx4 v[170:171], v[112:115], off offset:576
	v_fmamk_f32 v174, v247, 0x3a800000, v195
	v_mul_f32_e32 v175, 0x4b800000, v174
	v_cmp_gt_f32_e32 vcc, s44, v174
	s_nop 1
	v_cndmask_b32_e32 v174, v174, v175, vcc
	v_rsq_f32_e32 v146, v174
	s_nop 0
	v_mul_f32_e32 v175, 0x45800000, v146
	v_cndmask_b32_e32 v146, v146, v175, vcc
	v_pk_mul_f32 v[108:109], v[108:109], v[146:147] op_sel_hi:[1,0]
	v_pk_mul_f32 v[110:111], v[110:111], v[146:147] op_sel_hi:[1,0]
	v_pk_mul_f32 v[104:105], v[104:105], v[146:147] op_sel_hi:[1,0]
	v_pk_mul_f32 v[106:107], v[106:107], v[146:147] op_sel_hi:[1,0]
	v_pk_mul_f32 v[100:101], v[100:101], v[146:147] op_sel_hi:[1,0]
	v_pk_mul_f32 v[102:103], v[102:103], v[146:147] op_sel_hi:[1,0]
	v_pk_mul_f32 v[96:97], v[96:97], v[146:147] op_sel_hi:[1,0]
	v_pk_mul_f32 v[98:99], v[98:99], v[146:147] op_sel_hi:[1,0]
	v_pk_mul_f32 v[108:109], v[140:141], v[108:109]
	v_pk_mul_f32 v[110:111], v[142:143], v[110:111]
	v_pk_mul_f32 v[104:105], v[136:137], v[104:105]
	v_pk_mul_f32 v[106:107], v[138:139], v[106:107]
	v_pk_mul_f32 v[100:101], v[132:133], v[100:101]
	v_pk_mul_f32 v[102:103], v[134:135], v[102:103]
	v_pk_mul_f32 v[96:97], v[128:129], v[96:97]
	v_pk_mul_f32 v[98:99], v[130:131], v[98:99]
	s_mov_b64 s[100:101], 0x10000
	v_lshl_add_u64 v[172:173], v[170:171], 0, s[100:101]
	global_store_dwordx4 v[172:173], v[108:111], off
	global_store_dwordx4 v[172:173], v[104:107], off offset:64
	global_store_dwordx4 v[172:173], v[100:103], off offset:512
	global_store_dwordx4 v[172:173], v[96:99], off offset:576
	v_fmamk_f32 v174, v248, 0x3a800000, v195
	v_mul_f32_e32 v175, 0x4b800000, v174
	v_cmp_gt_f32_e32 vcc, s44, v174
	s_nop 1
	v_cndmask_b32_e32 v174, v174, v175, vcc
	v_rsq_f32_e32 v148, v174
	s_nop 0
	v_mul_f32_e32 v175, 0x45800000, v148
	v_cndmask_b32_e32 v148, v148, v175, vcc
	v_pk_mul_f32 v[92:93], v[92:93], v[148:149] op_sel_hi:[1,0]
	v_pk_mul_f32 v[94:95], v[94:95], v[148:149] op_sel_hi:[1,0]
	v_pk_mul_f32 v[88:89], v[88:89], v[148:149] op_sel_hi:[1,0]
	v_pk_mul_f32 v[90:91], v[90:91], v[148:149] op_sel_hi:[1,0]
	v_pk_mul_f32 v[84:85], v[84:85], v[148:149] op_sel_hi:[1,0]
	v_pk_mul_f32 v[86:87], v[86:87], v[148:149] op_sel_hi:[1,0]
	v_pk_mul_f32 v[80:81], v[80:81], v[148:149] op_sel_hi:[1,0]
	v_pk_mul_f32 v[82:83], v[82:83], v[148:149] op_sel_hi:[1,0]
	v_pk_mul_f32 v[92:93], v[140:141], v[92:93]
	v_pk_mul_f32 v[94:95], v[142:143], v[94:95]
	v_pk_mul_f32 v[88:89], v[136:137], v[88:89]
	v_pk_mul_f32 v[90:91], v[138:139], v[90:91]
	v_pk_mul_f32 v[84:85], v[132:133], v[84:85]
	v_pk_mul_f32 v[86:87], v[134:135], v[86:87]
	v_pk_mul_f32 v[80:81], v[128:129], v[80:81]
	v_pk_mul_f32 v[82:83], v[130:131], v[82:83]
	s_mov_b64 s[100:101], 0x20000
	v_lshl_add_u64 v[172:173], v[170:171], 0, s[100:101]
	global_store_dwordx4 v[172:173], v[92:95], off
	global_store_dwordx4 v[172:173], v[88:91], off offset:64
	global_store_dwordx4 v[172:173], v[84:87], off offset:512
	global_store_dwordx4 v[172:173], v[80:83], off offset:576
	v_fmamk_f32 v174, v249, 0x3a800000, v195
	v_mul_f32_e32 v175, 0x4b800000, v174
	v_cmp_gt_f32_e32 vcc, s44, v174
	s_nop 1
	v_cndmask_b32_e32 v174, v174, v175, vcc
	v_rsq_f32_e32 v150, v174
	s_nop 0
	v_mul_f32_e32 v175, 0x45800000, v150
	v_cndmask_b32_e32 v150, v150, v175, vcc
	v_pk_mul_f32 v[76:77], v[76:77], v[150:151] op_sel_hi:[1,0]
	v_pk_mul_f32 v[78:79], v[78:79], v[150:151] op_sel_hi:[1,0]
	v_pk_mul_f32 v[72:73], v[72:73], v[150:151] op_sel_hi:[1,0]
	v_pk_mul_f32 v[74:75], v[74:75], v[150:151] op_sel_hi:[1,0]
	v_pk_mul_f32 v[68:69], v[68:69], v[150:151] op_sel_hi:[1,0]
	v_pk_mul_f32 v[70:71], v[70:71], v[150:151] op_sel_hi:[1,0]
	v_pk_mul_f32 v[64:65], v[64:65], v[150:151] op_sel_hi:[1,0]
	v_pk_mul_f32 v[66:67], v[66:67], v[150:151] op_sel_hi:[1,0]
	v_pk_mul_f32 v[76:77], v[140:141], v[76:77]
	v_pk_mul_f32 v[78:79], v[142:143], v[78:79]
	v_pk_mul_f32 v[72:73], v[136:137], v[72:73]
	v_pk_mul_f32 v[74:75], v[138:139], v[74:75]
	v_pk_mul_f32 v[68:69], v[132:133], v[68:69]
	v_pk_mul_f32 v[70:71], v[134:135], v[70:71]
	v_pk_mul_f32 v[64:65], v[128:129], v[64:65]
	v_pk_mul_f32 v[66:67], v[130:131], v[66:67]
	s_mov_b64 s[100:101], 0x30000
	v_lshl_add_u64 v[172:173], v[170:171], 0, s[100:101]
	global_store_dwordx4 v[172:173], v[76:79], off
	global_store_dwordx4 v[172:173], v[72:75], off offset:64
	global_store_dwordx4 v[172:173], v[68:71], off offset:512
	global_store_dwordx4 v[172:173], v[64:67], off offset:576
	v_fmamk_f32 v174, v250, 0x3a800000, v195
	v_mul_f32_e32 v175, 0x4b800000, v174
	v_cmp_gt_f32_e32 vcc, s44, v174
	s_nop 1
	v_cndmask_b32_e32 v174, v174, v175, vcc
	v_rsq_f32_e32 v152, v174
	s_nop 0
	v_mul_f32_e32 v175, 0x45800000, v152
	v_cndmask_b32_e32 v152, v152, v175, vcc
	v_pk_mul_f32 v[60:61], v[60:61], v[152:153] op_sel_hi:[1,0]
	v_pk_mul_f32 v[62:63], v[62:63], v[152:153] op_sel_hi:[1,0]
	v_pk_mul_f32 v[56:57], v[56:57], v[152:153] op_sel_hi:[1,0]
	v_pk_mul_f32 v[58:59], v[58:59], v[152:153] op_sel_hi:[1,0]
	v_pk_mul_f32 v[52:53], v[52:53], v[152:153] op_sel_hi:[1,0]
	v_pk_mul_f32 v[54:55], v[54:55], v[152:153] op_sel_hi:[1,0]
	v_pk_mul_f32 v[44:45], v[44:45], v[152:153] op_sel_hi:[1,0]
	v_pk_mul_f32 v[46:47], v[46:47], v[152:153] op_sel_hi:[1,0]
	v_pk_mul_f32 v[60:61], v[140:141], v[60:61]
	v_pk_mul_f32 v[62:63], v[142:143], v[62:63]
	v_pk_mul_f32 v[56:57], v[136:137], v[56:57]
	v_pk_mul_f32 v[58:59], v[138:139], v[58:59]
	v_pk_mul_f32 v[52:53], v[132:133], v[52:53]
	v_pk_mul_f32 v[54:55], v[134:135], v[54:55]
	v_pk_mul_f32 v[44:45], v[128:129], v[44:45]
	v_pk_mul_f32 v[46:47], v[130:131], v[46:47]
	s_mov_b64 s[100:101], 0x80000
	v_lshl_add_u64 v[172:173], v[170:171], 0, s[100:101]
	global_store_dwordx4 v[172:173], v[60:63], off
	global_store_dwordx4 v[172:173], v[56:59], off offset:64
	global_store_dwordx4 v[172:173], v[52:55], off offset:512
	global_store_dwordx4 v[172:173], v[44:47], off offset:576
	v_fmamk_f32 v174, v251, 0x3a800000, v195
	v_mul_f32_e32 v175, 0x4b800000, v174
	v_cmp_gt_f32_e32 vcc, s44, v174
	s_nop 1
	v_cndmask_b32_e32 v174, v174, v175, vcc
	v_rsq_f32_e32 v154, v174
	s_nop 0
	v_mul_f32_e32 v175, 0x45800000, v154
	v_cndmask_b32_e32 v154, v154, v175, vcc
	v_pk_mul_f32 v[48:49], v[48:49], v[154:155] op_sel_hi:[1,0]
	v_pk_mul_f32 v[50:51], v[50:51], v[154:155] op_sel_hi:[1,0]
	v_pk_mul_f32 v[40:41], v[40:41], v[154:155] op_sel_hi:[1,0]
	v_pk_mul_f32 v[42:43], v[42:43], v[154:155] op_sel_hi:[1,0]
	v_pk_mul_f32 v[36:37], v[36:37], v[154:155] op_sel_hi:[1,0]
	v_pk_mul_f32 v[38:39], v[38:39], v[154:155] op_sel_hi:[1,0]
	v_pk_mul_f32 v[28:29], v[28:29], v[154:155] op_sel_hi:[1,0]
	v_pk_mul_f32 v[30:31], v[30:31], v[154:155] op_sel_hi:[1,0]
	v_pk_mul_f32 v[48:49], v[140:141], v[48:49]
	v_pk_mul_f32 v[50:51], v[142:143], v[50:51]
	v_pk_mul_f32 v[40:41], v[136:137], v[40:41]
	v_pk_mul_f32 v[42:43], v[138:139], v[42:43]
	v_pk_mul_f32 v[36:37], v[132:133], v[36:37]
	v_pk_mul_f32 v[38:39], v[134:135], v[38:39]
	v_pk_mul_f32 v[28:29], v[128:129], v[28:29]
	v_pk_mul_f32 v[30:31], v[130:131], v[30:31]
	s_mov_b64 s[100:101], 0x90000
	v_lshl_add_u64 v[172:173], v[170:171], 0, s[100:101]
	global_store_dwordx4 v[172:173], v[48:51], off
	global_store_dwordx4 v[172:173], v[40:43], off offset:64
	global_store_dwordx4 v[172:173], v[36:39], off offset:512
	global_store_dwordx4 v[172:173], v[28:31], off offset:576
	v_fmamk_f32 v174, v252, 0x3a800000, v195
	v_mul_f32_e32 v175, 0x4b800000, v174
	v_cmp_gt_f32_e32 vcc, s44, v174
	s_nop 1
	v_cndmask_b32_e32 v174, v174, v175, vcc
	v_rsq_f32_e32 v156, v174
	s_nop 0
	v_mul_f32_e32 v175, 0x45800000, v156
	v_cndmask_b32_e32 v156, v156, v175, vcc
	v_pk_mul_f32 v[32:33], v[32:33], v[156:157] op_sel_hi:[1,0]
	v_pk_mul_f32 v[34:35], v[34:35], v[156:157] op_sel_hi:[1,0]
	v_pk_mul_f32 v[24:25], v[24:25], v[156:157] op_sel_hi:[1,0]
	v_pk_mul_f32 v[26:27], v[26:27], v[156:157] op_sel_hi:[1,0]
	v_pk_mul_f32 v[20:21], v[20:21], v[156:157] op_sel_hi:[1,0]
	v_pk_mul_f32 v[22:23], v[22:23], v[156:157] op_sel_hi:[1,0]
	v_pk_mul_f32 v[16:17], v[16:17], v[156:157] op_sel_hi:[1,0]
	v_pk_mul_f32 v[18:19], v[18:19], v[156:157] op_sel_hi:[1,0]
	v_pk_mul_f32 v[32:33], v[140:141], v[32:33]
	v_pk_mul_f32 v[34:35], v[142:143], v[34:35]
	v_pk_mul_f32 v[24:25], v[136:137], v[24:25]
	v_pk_mul_f32 v[26:27], v[138:139], v[26:27]
	v_pk_mul_f32 v[20:21], v[132:133], v[20:21]
	v_pk_mul_f32 v[22:23], v[134:135], v[22:23]
	v_pk_mul_f32 v[16:17], v[128:129], v[16:17]
	v_pk_mul_f32 v[18:19], v[130:131], v[18:19]
	s_mov_b64 s[100:101], 0xa0000
	v_lshl_add_u64 v[172:173], v[170:171], 0, s[100:101]
	global_store_dwordx4 v[172:173], v[32:35], off
	global_store_dwordx4 v[172:173], v[24:27], off offset:64
	global_store_dwordx4 v[172:173], v[20:23], off offset:512
	global_store_dwordx4 v[172:173], v[16:19], off offset:576
	v_fmamk_f32 v174, v253, 0x3a800000, v195
	v_mul_f32_e32 v175, 0x4b800000, v174
	v_cmp_gt_f32_e32 vcc, s44, v174
	s_nop 1
	v_cndmask_b32_e32 v174, v174, v175, vcc
	v_rsq_f32_e32 v158, v174
	s_nop 0
	v_mul_f32_e32 v175, 0x45800000, v158
	v_cndmask_b32_e32 v158, v158, v175, vcc
	v_pk_mul_f32 v[12:13], v[12:13], v[158:159] op_sel_hi:[1,0]
	v_pk_mul_f32 v[14:15], v[14:15], v[158:159] op_sel_hi:[1,0]
	v_pk_mul_f32 v[8:9], v[8:9], v[158:159] op_sel_hi:[1,0]
	v_pk_mul_f32 v[10:11], v[10:11], v[158:159] op_sel_hi:[1,0]
	v_pk_mul_f32 v[4:5], v[4:5], v[158:159] op_sel_hi:[1,0]
	v_pk_mul_f32 v[6:7], v[6:7], v[158:159] op_sel_hi:[1,0]
	v_pk_mul_f32 v[0:1], v[0:1], v[158:159] op_sel_hi:[1,0]
	v_pk_mul_f32 v[2:3], v[2:3], v[158:159] op_sel_hi:[1,0]
	v_pk_mul_f32 v[12:13], v[140:141], v[12:13]
	v_pk_mul_f32 v[14:15], v[142:143], v[14:15]
	v_pk_mul_f32 v[8:9], v[136:137], v[8:9]
	v_pk_mul_f32 v[10:11], v[138:139], v[10:11]
	v_pk_mul_f32 v[4:5], v[132:133], v[4:5]
	v_pk_mul_f32 v[6:7], v[134:135], v[6:7]
	v_pk_mul_f32 v[0:1], v[128:129], v[0:1]
	v_pk_mul_f32 v[2:3], v[130:131], v[2:3]
	s_mov_b64 s[100:101], 0xb0000
	v_lshl_add_u64 v[172:173], v[170:171], 0, s[100:101]
	global_store_dwordx4 v[172:173], v[12:15], off
	global_store_dwordx4 v[172:173], v[8:11], off offset:64
	global_store_dwordx4 v[172:173], v[4:7], off offset:512
	global_store_dwordx4 v[172:173], v[0:3], off offset:576

.LBB0_742:
	s_waitcnt lgkmcnt(0)
	ds_read_b128 v[128:131], v190
	ds_read_b128 v[132:135], v190 offset:1024
	ds_read_b128 v[136:139], v190 offset:2048
	ds_read_b128 v[140:143], v190 offset:3072
	s_add_i32 s59, s58, 2
	s_cmpk_eq_i32 s57, 0xf00
	s_cselect_b32 s8, s23, s24
	s_cselect_b32 s9, 0, s59
	s_cselect_b32 s60, s26, s25
	s_and_b32 s52, s56, 0x4000000
	s_and_b32 s53, s57, 0x700
	s_add_u32 s52, s27, s52
	s_addc_u32 s61, s55, 0
	s_add_u32 s52, s52, s53
	s_addc_u32 s53, s61, 0
	v_lshl_add_u64 v[184:185], s[52:53], 0, v[160:161]
	s_mov_b32 m0, s40
	v_lshl_add_u64 v[184:185], v[184:185], 0, s[4:5]
	ds_read_b128 v[144:147], v191
	ds_read_b128 v[148:151], v191 offset:1024
	ds_read_b128 v[152:155], v191 offset:2048
	ds_read_b128 v[156:159], v191 offset:3072
	ds_read_b128 v[168:171], v191 offset:4096
	ds_read_b128 v[172:175], v191 offset:5120
	ds_read_b128 v[176:179], v191 offset:6144
	ds_read_b128 v[180:183], v191 offset:7168
	global_load_lds_dwordx4 v[184:185], off
	v_lshl_add_u64 v[184:185], s[52:53], 0, v[164:165]
	v_lshl_add_u64 v[184:185], v[184:185], 0, s[4:5]
	s_mov_b32 m0, s41
	s_nop 0
	global_load_lds_dwordx4 v[184:185], off
	s_waitcnt lgkmcnt(8)
	s_barrier
	s_waitcnt lgkmcnt(0)
	s_setprio 1
	s_waitcnt lgkmcnt(0)
	v_mfma_f32_16x16x32_bf16 v[124:127], v[128:131], v[144:147], v[124:127]
	v_mfma_f32_16x16x32_bf16 v[120:123], v[136:139], v[144:147], v[120:123]
	v_mfma_f32_16x16x32_bf16 v[108:111], v[128:131], v[152:155], v[108:111]
	v_mfma_f32_16x16x32_bf16 v[104:107], v[136:139], v[152:155], v[104:107]
	v_mfma_f32_16x16x32_bf16 v[92:95], v[128:131], v[168:171], v[92:95]
	v_mfma_f32_16x16x32_bf16 v[88:91], v[136:139], v[168:171], v[88:91]
	v_mfma_f32_16x16x32_bf16 v[76:79], v[128:131], v[176:179], v[76:79]
	v_mfma_f32_16x16x32_bf16 v[72:75], v[136:139], v[176:179], v[72:75]
	v_mfma_f32_16x16x32_bf16 v[124:127], v[132:135], v[148:151], v[124:127]
	v_mfma_f32_16x16x32_bf16 v[120:123], v[140:143], v[148:151], v[120:123]
	v_mfma_f32_16x16x32_bf16 v[108:111], v[132:135], v[156:159], v[108:111]
	v_mfma_f32_16x16x32_bf16 v[104:107], v[140:143], v[156:159], v[104:107]
	v_mfma_f32_16x16x32_bf16 v[92:95], v[132:135], v[172:175], v[92:95]
	v_mfma_f32_16x16x32_bf16 v[88:91], v[140:143], v[172:175], v[88:91]
	v_mfma_f32_16x16x32_bf16 v[76:79], v[132:135], v[180:183], v[76:79]
	v_mfma_f32_16x16x32_bf16 v[72:75], v[140:143], v[180:183], v[72:75]
	s_setprio 0
	s_barrier
	s_lshl_b32 s52, s60, 8
	s_ashr_i32 s53, s52, 31
	s_lshl_b32 s64, s9, 7
	s_lshl_b64 s[60:61], s[52:53], 12
	s_add_u32 s53, s86, s60
	s_addc_u32 s61, s87, s61
	s_add_u32 s60, s53, s64
	s_addc_u32 s61, s61, 0
	s_mov_b32 m0, s42
	v_lshl_add_u64 v[202:203], s[60:61], 0, v[162:163]
	ds_read_b128 v[184:187], v193
	ds_read_b128 v[198:201], v193 offset:1024
	ds_read_b128 v[206:209], v193 offset:2048
	ds_read_b128 v[210:213], v193 offset:3072
	global_load_lds_dwordx4 v[202:203], off
	v_lshl_add_u64 v[214:215], s[60:61], 0, v[166:167]
	s_mov_b32 m0, s43
	s_nop 0
	global_load_lds_dwordx4 v[214:215], off
	s_barrier
	s_waitcnt lgkmcnt(0)
	s_setprio 1
	s_waitcnt lgkmcnt(0)
	v_mfma_f32_16x16x32_bf16 v[116:119], v[184:187], v[144:147], v[116:119]
	v_mfma_f32_16x16x32_bf16 v[112:115], v[206:209], v[144:147], v[112:115]
	v_mfma_f32_16x16x32_bf16 v[100:103], v[184:187], v[152:155], v[100:103]
	v_mfma_f32_16x16x32_bf16 v[96:99], v[206:209], v[152:155], v[96:99]
	v_mfma_f32_16x16x32_bf16 v[84:87], v[184:187], v[168:171], v[84:87]
	v_mfma_f32_16x16x32_bf16 v[80:83], v[206:209], v[168:171], v[80:83]
	v_mfma_f32_16x16x32_bf16 v[68:71], v[184:187], v[176:179], v[68:71]
	v_mfma_f32_16x16x32_bf16 v[64:67], v[206:209], v[176:179], v[64:67]
	v_mfma_f32_16x16x32_bf16 v[116:119], v[198:201], v[148:151], v[116:119]
	v_mfma_f32_16x16x32_bf16 v[112:115], v[210:213], v[148:151], v[112:115]
	v_mfma_f32_16x16x32_bf16 v[100:103], v[198:201], v[156:159], v[100:103]
	v_mfma_f32_16x16x32_bf16 v[96:99], v[210:213], v[156:159], v[96:99]
	v_mfma_f32_16x16x32_bf16 v[84:87], v[198:201], v[172:175], v[84:87]
	v_mfma_f32_16x16x32_bf16 v[80:83], v[210:213], v[172:175], v[80:83]
	v_mfma_f32_16x16x32_bf16 v[68:71], v[198:201], v[180:183], v[68:71]
	v_mfma_f32_16x16x32_bf16 v[64:67], v[210:213], v[180:183], v[64:67]
	s_setprio 0
	s_lshl_b32 s9, s9, 22
	s_and_b32 s9, s9, 0xc000000
	s_add_u32 s9, s38, s9
	s_addc_u32 s65, s39, 0
	s_lshl_b32 s60, s8, 8
	s_ashr_i32 s61, s60, 31
	s_and_b32 s8, s64, 0x700
	s_lshl_b64 s[62:63], s[60:61], 11
	s_add_u32 s61, s9, s62
	s_addc_u32 s66, s65, s63
	s_add_u32 s62, s61, s8
	s_addc_u32 s63, s66, 0
	s_mov_b32 m0, s3
	v_lshl_add_u64 v[216:217], s[62:63], 0, v[160:161]
	s_barrier
	ds_read_b128 v[144:147], v191 offset:16384
	ds_read_b128 v[148:151], v191 offset:17408
	ds_read_b128 v[152:155], v191 offset:18432
	ds_read_b128 v[156:159], v191 offset:19456
	ds_read_b128 v[168:171], v191 offset:20480
	ds_read_b128 v[172:175], v191 offset:21504
	ds_read_b128 v[176:179], v191 offset:22528
	ds_read_b128 v[180:183], v191 offset:23552
	global_load_lds_dwordx4 v[216:217], off
	v_lshl_add_u64 v[216:217], s[62:63], 0, v[164:165]
	s_mov_b32 m0, s10
	s_nop 0
	global_load_lds_dwordx4 v[216:217], off
	s_barrier
	s_waitcnt lgkmcnt(0)
	s_setprio 1
	s_waitcnt lgkmcnt(0)
	v_mfma_f32_16x16x32_bf16 v[60:63], v[128:131], v[144:147], v[60:63]
	v_mfma_f32_16x16x32_bf16 v[56:59], v[136:139], v[144:147], v[56:59]
	v_mfma_f32_16x16x32_bf16 v[48:51], v[128:131], v[152:155], v[48:51]
	v_mfma_f32_16x16x32_bf16 v[40:43], v[136:139], v[152:155], v[40:43]
	v_mfma_f32_16x16x32_bf16 v[32:35], v[128:131], v[168:171], v[32:35]
	v_mfma_f32_16x16x32_bf16 v[24:27], v[136:139], v[168:171], v[24:27]
	v_mfma_f32_16x16x32_bf16 v[12:15], v[128:131], v[176:179], v[12:15]
	v_mfma_f32_16x16x32_bf16 v[8:11], v[136:139], v[176:179], v[8:11]
	v_mfma_f32_16x16x32_bf16 v[60:63], v[132:135], v[148:151], v[60:63]
	v_mfma_f32_16x16x32_bf16 v[56:59], v[140:143], v[148:151], v[56:59]
	v_mfma_f32_16x16x32_bf16 v[48:51], v[132:135], v[156:159], v[48:51]
	v_mfma_f32_16x16x32_bf16 v[40:43], v[140:143], v[156:159], v[40:43]
	v_mfma_f32_16x16x32_bf16 v[32:35], v[132:135], v[172:175], v[32:35]
	v_mfma_f32_16x16x32_bf16 v[24:27], v[140:143], v[172:175], v[24:27]
	v_mfma_f32_16x16x32_bf16 v[12:15], v[132:135], v[180:183], v[12:15]
	v_mfma_f32_16x16x32_bf16 v[8:11], v[140:143], v[180:183], v[8:11]
	s_setprio 0
	s_barrier
	s_bitset1_b32 s52, 7
	s_ashr_i32 s53, s52, 31
	s_lshl_b64 s[52:53], s[52:53], 12
	s_add_u32 s52, s86, s52
	s_addc_u32 s53, s87, s53
	s_add_u32 s52, s52, s64
	s_addc_u32 s53, s53, 0
	s_mov_b32 m0, s45
	v_lshl_add_u64 v[216:217], s[52:53], 0, v[162:163]
	global_load_lds_dwordx4 v[216:217], off
	v_lshl_add_u64 v[218:219], s[52:53], 0, v[166:167]
	s_mov_b32 m0, s46
	s_nop 0
	global_load_lds_dwordx4 v[218:219], off
	s_waitcnt vmcnt(6)
	s_barrier
	s_setprio 1
	v_mfma_f32_16x16x32_bf16 v[52:55], v[184:187], v[144:147], v[52:55]
	v_mfma_f32_16x16x32_bf16 v[44:47], v[206:209], v[144:147], v[44:47]
	v_mfma_f32_16x16x32_bf16 v[36:39], v[184:187], v[152:155], v[36:39]
	v_mfma_f32_16x16x32_bf16 v[28:31], v[206:209], v[152:155], v[28:31]
	v_mfma_f32_16x16x32_bf16 v[20:23], v[184:187], v[168:171], v[20:23]
	v_mfma_f32_16x16x32_bf16 v[16:19], v[206:209], v[168:171], v[16:19]
	v_mfma_f32_16x16x32_bf16 v[4:7], v[184:187], v[176:179], v[4:7]
	v_mfma_f32_16x16x32_bf16 v[0:3], v[206:209], v[176:179], v[0:3]
	v_mfma_f32_16x16x32_bf16 v[52:55], v[198:201], v[148:151], v[52:55]
	v_mfma_f32_16x16x32_bf16 v[44:47], v[210:213], v[148:151], v[44:47]
	v_mfma_f32_16x16x32_bf16 v[36:39], v[198:201], v[156:159], v[36:39]
	v_mfma_f32_16x16x32_bf16 v[28:31], v[210:213], v[156:159], v[28:31]
	v_mfma_f32_16x16x32_bf16 v[20:23], v[198:201], v[172:175], v[20:23]
	v_mfma_f32_16x16x32_bf16 v[16:19], v[210:213], v[172:175], v[16:19]
	v_mfma_f32_16x16x32_bf16 v[4:7], v[198:201], v[180:183], v[4:7]
	v_mfma_f32_16x16x32_bf16 v[0:3], v[210:213], v[180:183], v[0:3]
	s_setprio 0
	s_barrier
	ds_read_b128 v[128:131], v196
	ds_read_b128 v[132:135], v196 offset:1024
	ds_read_b128 v[136:139], v196 offset:2048
	ds_read_b128 v[140:143], v196 offset:3072
	s_or_b32 s52, s60, 0x80
	s_ashr_i32 s53, s52, 31
	s_lshl_b64 s[52:53], s[52:53], 11
	s_add_u32 s9, s9, s52
	s_addc_u32 s53, s65, s53
	s_add_u32 s52, s9, s8
	s_addc_u32 s53, s53, 0
	s_mov_b32 m0, s11
	v_lshl_add_u64 v[184:185], s[52:53], 0, v[160:161]
	ds_read_b128 v[144:147], v191 offset:32768
	ds_read_b128 v[148:151], v191 offset:33792
	ds_read_b128 v[152:155], v191 offset:34816
	ds_read_b128 v[156:159], v191 offset:35840
	ds_read_b128 v[168:171], v191 offset:36864
	ds_read_b128 v[172:175], v191 offset:37888
	ds_read_b128 v[176:179], v191 offset:38912
	ds_read_b128 v[180:183], v191 offset:39936
	global_load_lds_dwordx4 v[184:185], off
	v_lshl_add_u64 v[184:185], s[52:53], 0, v[164:165]
	s_mov_b32 m0, s30
	s_nop 0
	global_load_lds_dwordx4 v[184:185], off
	s_waitcnt lgkmcnt(8)
	s_barrier
	s_waitcnt lgkmcnt(0)
	s_setprio 1
	s_waitcnt lgkmcnt(0)
	v_mfma_f32_16x16x32_bf16 v[124:127], v[128:131], v[144:147], v[124:127]
	v_mfma_f32_16x16x32_bf16 v[120:123], v[136:139], v[144:147], v[120:123]
	v_mfma_f32_16x16x32_bf16 v[108:111], v[128:131], v[152:155], v[108:111]
	v_mfma_f32_16x16x32_bf16 v[104:107], v[136:139], v[152:155], v[104:107]
	v_mfma_f32_16x16x32_bf16 v[92:95], v[128:131], v[168:171], v[92:95]
	v_mfma_f32_16x16x32_bf16 v[88:91], v[136:139], v[168:171], v[88:91]
	v_mfma_f32_16x16x32_bf16 v[76:79], v[128:131], v[176:179], v[76:79]
	v_mfma_f32_16x16x32_bf16 v[72:75], v[136:139], v[176:179], v[72:75]
	v_mfma_f32_16x16x32_bf16 v[124:127], v[132:135], v[148:151], v[124:127]
	v_mfma_f32_16x16x32_bf16 v[120:123], v[140:143], v[148:151], v[120:123]
	v_mfma_f32_16x16x32_bf16 v[108:111], v[132:135], v[156:159], v[108:111]
	v_mfma_f32_16x16x32_bf16 v[104:107], v[140:143], v[156:159], v[104:107]
	v_mfma_f32_16x16x32_bf16 v[92:95], v[132:135], v[172:175], v[92:95]
	v_mfma_f32_16x16x32_bf16 v[88:91], v[140:143], v[172:175], v[88:91]
	v_mfma_f32_16x16x32_bf16 v[76:79], v[132:135], v[180:183], v[76:79]
	v_mfma_f32_16x16x32_bf16 v[72:75], v[140:143], v[180:183], v[72:75]
	s_setprio 0
	s_barrier
	s_mov_b32 m0, s47
	v_lshl_add_u64 v[202:203], v[202:203], 0, s[4:5]
	ds_read_b128 v[184:187], v197
	ds_read_b128 v[198:201], v197 offset:1024
	ds_read_b128 v[206:209], v197 offset:2048
	ds_read_b128 v[210:213], v197 offset:3072
	global_load_lds_dwordx4 v[202:203], off
	v_lshl_add_u64 v[202:203], v[214:215], 0, s[4:5]
	s_mov_b32 m0, s48
	s_bitset1_b32 s64, 7
	global_load_lds_dwordx4 v[202:203], off
	s_barrier
	s_waitcnt lgkmcnt(0)
	s_setprio 1
	s_waitcnt lgkmcnt(0)
	v_mfma_f32_16x16x32_bf16 v[116:119], v[184:187], v[144:147], v[116:119]
	v_mfma_f32_16x16x32_bf16 v[112:115], v[206:209], v[144:147], v[112:115]
	v_mfma_f32_16x16x32_bf16 v[100:103], v[184:187], v[152:155], v[100:103]
	v_mfma_f32_16x16x32_bf16 v[96:99], v[206:209], v[152:155], v[96:99]
	v_mfma_f32_16x16x32_bf16 v[84:87], v[184:187], v[168:171], v[84:87]
	v_mfma_f32_16x16x32_bf16 v[80:83], v[206:209], v[168:171], v[80:83]
	v_mfma_f32_16x16x32_bf16 v[68:71], v[184:187], v[176:179], v[68:71]
	v_mfma_f32_16x16x32_bf16 v[64:67], v[206:209], v[176:179], v[64:67]
	v_mfma_f32_16x16x32_bf16 v[116:119], v[198:201], v[148:151], v[116:119]
	v_mfma_f32_16x16x32_bf16 v[112:115], v[210:213], v[148:151], v[112:115]
	v_mfma_f32_16x16x32_bf16 v[100:103], v[198:201], v[156:159], v[100:103]
	v_mfma_f32_16x16x32_bf16 v[96:99], v[210:213], v[156:159], v[96:99]
	v_mfma_f32_16x16x32_bf16 v[84:87], v[198:201], v[172:175], v[84:87]
	v_mfma_f32_16x16x32_bf16 v[80:83], v[210:213], v[172:175], v[80:83]
	v_mfma_f32_16x16x32_bf16 v[68:71], v[198:201], v[180:183], v[68:71]
	v_mfma_f32_16x16x32_bf16 v[64:67], v[210:213], v[180:183], v[64:67]
	s_setprio 0
	s_and_b32 s8, s64, 0x780
	s_add_u32 s52, s61, s8
	s_addc_u32 s53, s66, 0
	s_mov_b32 m0, s34
	v_lshl_add_u64 v[202:203], s[52:53], 0, v[160:161]
	s_barrier
	ds_read_b128 v[144:147], v191 offset:49152
	ds_read_b128 v[148:151], v191 offset:50176
	ds_read_b128 v[152:155], v191 offset:51200
	ds_read_b128 v[156:159], v191 offset:52224
	ds_read_b128 v[168:171], v191 offset:53248
	ds_read_b128 v[172:175], v191 offset:54272
	ds_read_b128 v[176:179], v191 offset:55296
	ds_read_b128 v[180:183], v191 offset:56320
	global_load_lds_dwordx4 v[202:203], off
	v_lshl_add_u64 v[202:203], s[52:53], 0, v[164:165]
	s_mov_b32 m0, s35
	s_nop 0
	global_load_lds_dwordx4 v[202:203], off
	s_barrier
	s_waitcnt lgkmcnt(0)
	s_setprio 1
	s_waitcnt lgkmcnt(0)
	v_mfma_f32_16x16x32_bf16 v[60:63], v[128:131], v[144:147], v[60:63]
	v_mfma_f32_16x16x32_bf16 v[56:59], v[136:139], v[144:147], v[56:59]
	v_mfma_f32_16x16x32_bf16 v[48:51], v[128:131], v[152:155], v[48:51]
	v_mfma_f32_16x16x32_bf16 v[40:43], v[136:139], v[152:155], v[40:43]
	v_mfma_f32_16x16x32_bf16 v[32:35], v[128:131], v[168:171], v[32:35]
	v_mfma_f32_16x16x32_bf16 v[24:27], v[136:139], v[168:171], v[24:27]
	v_mfma_f32_16x16x32_bf16 v[12:15], v[128:131], v[176:179], v[12:15]
	v_mfma_f32_16x16x32_bf16 v[8:11], v[136:139], v[176:179], v[8:11]
	v_mfma_f32_16x16x32_bf16 v[60:63], v[132:135], v[148:151], v[60:63]
	v_mfma_f32_16x16x32_bf16 v[56:59], v[140:143], v[148:151], v[56:59]
	v_mfma_f32_16x16x32_bf16 v[48:51], v[132:135], v[156:159], v[48:51]
	v_mfma_f32_16x16x32_bf16 v[40:43], v[140:143], v[156:159], v[40:43]
	v_mfma_f32_16x16x32_bf16 v[32:35], v[132:135], v[172:175], v[32:35]
	v_mfma_f32_16x16x32_bf16 v[24:27], v[140:143], v[172:175], v[24:27]
	v_mfma_f32_16x16x32_bf16 v[12:15], v[132:135], v[180:183], v[12:15]
	v_mfma_f32_16x16x32_bf16 v[8:11], v[140:143], v[180:183], v[8:11]
	s_setprio 0
	s_barrier
	s_mov_b32 m0, s49
	v_lshl_add_u64 v[128:129], v[216:217], 0, s[4:5]
	global_load_lds_dwordx4 v[128:129], off
	v_lshl_add_u64 v[128:129], v[218:219], 0, s[4:5]
	s_mov_b32 m0, s50
	s_nop 0
	global_load_lds_dwordx4 v[128:129], off
	s_waitcnt vmcnt(6)
	s_barrier
	s_setprio 1
	v_mfma_f32_16x16x32_bf16 v[52:55], v[184:187], v[144:147], v[52:55]
	v_mfma_f32_16x16x32_bf16 v[44:47], v[206:209], v[144:147], v[44:47]
	v_mfma_f32_16x16x32_bf16 v[36:39], v[184:187], v[152:155], v[36:39]
	v_mfma_f32_16x16x32_bf16 v[28:31], v[206:209], v[152:155], v[28:31]
	v_mfma_f32_16x16x32_bf16 v[20:23], v[184:187], v[168:171], v[20:23]
	v_mfma_f32_16x16x32_bf16 v[16:19], v[206:209], v[168:171], v[16:19]
	v_mfma_f32_16x16x32_bf16 v[4:7], v[184:187], v[176:179], v[4:7]
	v_mfma_f32_16x16x32_bf16 v[0:3], v[206:209], v[176:179], v[0:3]
	v_mfma_f32_16x16x32_bf16 v[52:55], v[198:201], v[148:151], v[52:55]
	v_mfma_f32_16x16x32_bf16 v[44:47], v[210:213], v[148:151], v[44:47]
	v_mfma_f32_16x16x32_bf16 v[36:39], v[198:201], v[156:159], v[36:39]
	v_mfma_f32_16x16x32_bf16 v[28:31], v[210:213], v[156:159], v[28:31]
	v_mfma_f32_16x16x32_bf16 v[20:23], v[198:201], v[172:175], v[20:23]
	v_mfma_f32_16x16x32_bf16 v[16:19], v[210:213], v[172:175], v[16:19]
	v_mfma_f32_16x16x32_bf16 v[4:7], v[198:201], v[180:183], v[4:7]
	v_mfma_f32_16x16x32_bf16 v[0:3], v[210:213], v[180:183], v[0:3]
	s_setprio 0
	s_addk_i32 s57, 0x100
	s_add_i32 s56, s56, 0x800000
	s_cmp_gt_u32 s58, 29
	s_mov_b32 s58, s59
	s_barrier
	s_cbranch_scc0 .LBB0_742
	s_and_b64 vcc, exec, s[74:75]
	s_cbranch_vccnz .Lout_fused_epi
	s_lshr_b32 s8, s24, 4
	v_readlane_b32 s56, v241, 0
	s_mul_i32 s26, s8, 0xc00
	v_readlane_b32 s57, v241, 1
	s_ashr_i32 s27, s26, 31
	v_readlane_b32 s58, v241, 2
	v_readlane_b32 s59, v241, 3
	v_readlane_b32 s60, v241, 4
	v_readlane_b32 s61, v241, 5
	s_mov_b64 s[16:17], s[56:57]
	s_lshl_b64 s[26:27], s[26:27], 2
	s_mov_b64 s[18:19], s[58:59]
	v_lshl_or_b32 v170, s25, 8, v189
	s_add_u32 s26, s18, s26
	s_addc_u32 s27, s19, s27
	v_ashrrev_i32_e32 v171, 31, v170
	v_lshl_add_u64 v[128:129], v[170:171], 2, s[26:27]
	v_readlane_b32 s62, v241, 6
	v_readlane_b32 s63, v241, 7
	v_readlane_b32 s64, v241, 8
	v_readlane_b32 s65, v241, 9
	v_readlane_b32 s66, v241, 10
	v_readlane_b32 s67, v241, 11
	v_readlane_b32 s68, v241, 12
	v_readlane_b32 s69, v241, 13
	v_readlane_b32 s70, v241, 14
	v_readlane_b32 s71, v241, 15
	v_lshl_add_u64 v[130:131], v[128:129], 0, s[12:13]
	v_add_co_u32_e32 v128, vcc, s31, v128
	v_add_u32_e32 v172, s22, v188
	s_mov_b64 s[20:21], s[60:61]
	v_addc_co_u32_e32 v129, vcc, 0, v129, vcc
	v_ashrrev_i32_e32 v173, 31, v172
	v_readlane_b32 s56, v241, 55
	global_load_dwordx4 v[140:143], v[128:129], off
	v_lshlrev_b64 v[128:129], 10, v[172:173]
	v_readlane_b32 s57, v241, 56
	v_lshl_add_u64 v[148:149], v[128:129], 0, v[170:171]
	s_mov_b64 s[8:9], s[56:57]
	v_lshl_add_u64 v[156:157], v[148:149], 2, s[8:9]
	global_load_dwordx4 v[144:147], v[156:157], off
	global_load_dwordx4 v[136:139], v[130:131], off offset:64
	global_load_dwordx4 v[132:135], v[130:131], off offset:512
	s_nop 0
	global_load_dwordx4 v[128:131], v[130:131], off offset:576
	s_and_b64 vcc, exec, s[74:75]
	v_lshl_add_u64 v[168:169], v[148:149], 2, s[16:17]
	v_readlane_b32 s58, v241, 57
	v_readlane_b32 s59, v241, 58
	v_readlane_b32 s60, v241, 59
	v_readlane_b32 s61, v241, 60
	v_readlane_b32 s62, v241, 61
	v_readlane_b32 s63, v241, 62
	v_readlane_b32 s64, v241, 63
	v_readlane_b32 s65, v240, 0
	v_readlane_b32 s66, v240, 1
	v_readlane_b32 s67, v240, 2
	v_readlane_b32 s68, v240, 3
	v_readlane_b32 s69, v240, 4
	v_readlane_b32 s70, v240, 5
	v_readlane_b32 s71, v240, 6
	s_waitcnt vmcnt(0)
	v_pk_fma_f32 v[146:147], v[126:127], v[142:143], v[146:147]
	v_pk_fma_f32 v[144:145], v[124:125], v[140:141], v[144:145]
	s_cbranch_vccnz .LBB0_745
	global_store_dwordx4 v[168:169], v[144:147], off
	s_branch .LBB0_746

.Lout_fused_epi:
	s_lshr_b32 s8, s24, 4
	s_mul_i32 s26, s8, 0xc00
	v_readlane_b32 s18, v241, 2
	v_readlane_b32 s19, v241, 3
	s_ashr_i32 s27, s26, 31
	v_readlane_b32 s20, v241, 4
	v_readlane_b32 s21, v241, 5
	s_lshl_b64 s[26:27], s[26:27], 2
	v_readlane_b32 s8, v241, 55
	v_readlane_b32 s9, v241, 56
	v_readlane_b32 s70, v241, 48
	v_readlane_b32 s71, v241, 49
	v_lshl_or_b32 v170, s25, 8, v189
	v_ashrrev_i32_e32 v171, 31, v170
	v_add_u32_e32 v172, s22, v188
	v_ashrrev_i32_e32 v173, 31, v172
	s_add_u32 s26, s18, s26
	s_addc_u32 s27, s19, s27
	s_add_u32 s26, s26, 0x2000
	s_addc_u32 s27, s27, 0
	v_lshl_add_u64 v[204:205], v[170:171], 2, s[26:27]
	global_load_dwordx4 v[140:143], v[204:205], off
	global_load_dwordx4 v[136:139], v[204:205], off offset:64
	global_load_dwordx4 v[132:135], v[204:205], off offset:512
	global_load_dwordx4 v[128:131], v[204:205], off offset:576
	v_lshlrev_b64 v[186:187], 10, v[172:173]
	v_lshl_add_u64 v[186:187], v[186:187], 0, v[170:171]
	v_lshlrev_b64 v[186:187], 2, v[186:187]
	v_lshl_add_u64 v[254:255], v[170:171], 2, s[70:71]
	v_lshl_add_u64 v[168:169], v[172:173], 2, s[20:21]
	v_lshl_add_u64 v[170:171], v[186:187], 0, s[8:9]
	global_load_dwordx4 v[144:147], v[170:171], off
	global_load_dwordx4 v[148:151], v[170:171], off offset:64
	global_load_dwordx4 v[152:155], v[170:171], off offset:512
	global_load_dwordx4 v[156:159], v[170:171], off offset:576
	s_mov_b64 s[100:101], 0x10000
	v_lshl_add_u64 v[172:173], v[170:171], 0, s[100:101]
	global_load_dwordx4 v[174:177], v[172:173], off
	global_load_dwordx4 v[178:181], v[172:173], off offset:64
	global_load_dwordx4 v[182:185], v[172:173], off offset:512
	global_load_dwordx4 v[198:201], v[172:173], off offset:576
	s_mov_b64 s[100:101], 0x20000
	v_lshl_add_u64 v[172:173], v[170:171], 0, s[100:101]
	global_load_dwordx4 v[206:209], v[172:173], off
	global_load_dwordx4 v[210:213], v[172:173], off offset:64
	global_load_dwordx4 v[220:223], v[172:173], off offset:512
	global_load_dwordx4 v[224:227], v[172:173], off offset:576
	s_mov_b64 s[100:101], 0x30000
	v_lshl_add_u64 v[172:173], v[170:171], 0, s[100:101]
	global_load_dwordx4 v[228:231], v[172:173], off
	global_load_dwordx4 v[232:235], v[172:173], off offset:64
	global_load_dwordx4 v[236:239], v[172:173], off offset:512
	global_load_dwordx4 v[242:245], v[172:173], off offset:576
	s_waitcnt vmcnt(12)
	v_pk_fma_f32 v[126:127], v[126:127], v[142:143], v[146:147]
	v_pk_fma_f32 v[124:125], v[124:125], v[140:141], v[144:145]
	v_pk_fma_f32 v[122:123], v[122:123], v[138:139], v[150:151]
	v_pk_fma_f32 v[120:121], v[120:121], v[136:137], v[148:149]
	v_pk_fma_f32 v[118:119], v[118:119], v[134:135], v[154:155]
	v_pk_fma_f32 v[116:117], v[116:117], v[132:133], v[152:153]
	v_pk_fma_f32 v[114:115], v[114:115], v[130:131], v[158:159]
	v_pk_fma_f32 v[112:113], v[112:113], v[128:129], v[156:157]
	v_mul_f32_e32 v145, v125, v125
	v_fmac_f32_e32 v145, v124, v124
	v_mul_f32_e32 v147, v127, v127
	v_fmac_f32_e32 v147, v126, v126
	v_add_f32_e32 v246, v145, v147
	v_mul_f32_e32 v149, v121, v121
	v_mul_f32_e32 v151, v123, v123
	v_fmac_f32_e32 v149, v120, v120
	v_fmac_f32_e32 v151, v122, v122
	v_add_f32_e32 v149, v149, v151
	v_add_f32_e32 v246, v246, v149
	v_mul_f32_e32 v153, v117, v117
	v_mul_f32_e32 v155, v119, v119
	v_fmac_f32_e32 v153, v116, v116
	v_fmac_f32_e32 v155, v118, v118
	v_add_f32_e32 v153, v153, v155
	v_add_f32_e32 v246, v246, v153
	v_mul_f32_e32 v157, v113, v113
	v_mul_f32_e32 v159, v115, v115
	v_fmac_f32_e32 v157, v112, v112
	v_fmac_f32_e32 v159, v114, v114
	v_add_f32_e32 v157, v157, v159
	v_add_f32_e32 v246, v246, v157
	s_mov_b64 s[100:101], 0x80000
	v_lshl_add_u64 v[172:173], v[170:171], 0, s[100:101]
	global_load_dwordx4 v[144:147], v[172:173], off
	global_load_dwordx4 v[148:151], v[172:173], off offset:64
	global_load_dwordx4 v[152:155], v[172:173], off offset:512
	global_load_dwordx4 v[156:159], v[172:173], off offset:576
	s_waitcnt vmcnt(12)
	v_pk_fma_f32 v[110:111], v[110:111], v[142:143], v[176:177]
	v_pk_fma_f32 v[108:109], v[108:109], v[140:141], v[174:175]
	v_pk_fma_f32 v[106:107], v[106:107], v[138:139], v[180:181]
	v_pk_fma_f32 v[104:105], v[104:105], v[136:137], v[178:179]
	v_pk_fma_f32 v[102:103], v[102:103], v[134:135], v[184:185]
	v_pk_fma_f32 v[100:101], v[100:101], v[132:133], v[182:183]
	v_pk_fma_f32 v[98:99], v[98:99], v[130:131], v[200:201]
	v_pk_fma_f32 v[96:97], v[96:97], v[128:129], v[198:199]
	v_mul_f32_e32 v175, v109, v109
	v_fmac_f32_e32 v175, v108, v108
	v_mul_f32_e32 v177, v111, v111
	v_fmac_f32_e32 v177, v110, v110
	v_add_f32_e32 v247, v175, v177
	v_mul_f32_e32 v179, v105, v105
	v_mul_f32_e32 v181, v107, v107
	v_fmac_f32_e32 v179, v104, v104
	v_fmac_f32_e32 v181, v106, v106
	v_add_f32_e32 v179, v179, v181
	v_add_f32_e32 v247, v247, v179
	v_mul_f32_e32 v183, v101, v101
	v_mul_f32_e32 v185, v103, v103
	v_fmac_f32_e32 v183, v100, v100
	v_fmac_f32_e32 v185, v102, v102
	v_add_f32_e32 v183, v183, v185
	v_add_f32_e32 v247, v247, v183
	v_mul_f32_e32 v199, v97, v97
	v_mul_f32_e32 v201, v99, v99
	v_fmac_f32_e32 v199, v96, v96
	v_fmac_f32_e32 v201, v98, v98
	v_add_f32_e32 v199, v199, v201
	v_add_f32_e32 v247, v247, v199
	s_mov_b64 s[100:101], 0x90000
	v_lshl_add_u64 v[172:173], v[170:171], 0, s[100:101]
	global_load_dwordx4 v[174:177], v[172:173], off
	global_load_dwordx4 v[178:181], v[172:173], off offset:64
	global_load_dwordx4 v[182:185], v[172:173], off offset:512
	global_load_dwordx4 v[198:201], v[172:173], off offset:576
	s_waitcnt vmcnt(12)
	v_pk_fma_f32 v[94:95], v[94:95], v[142:143], v[208:209]
	v_pk_fma_f32 v[92:93], v[92:93], v[140:141], v[206:207]
	v_pk_fma_f32 v[90:91], v[90:91], v[138:139], v[212:213]
	v_pk_fma_f32 v[88:89], v[88:89], v[136:137], v[210:211]
	v_pk_fma_f32 v[86:87], v[86:87], v[134:135], v[222:223]
	v_pk_fma_f32 v[84:85], v[84:85], v[132:133], v[220:221]
	v_pk_fma_f32 v[82:83], v[82:83], v[130:131], v[226:227]
	v_pk_fma_f32 v[80:81], v[80:81], v[128:129], v[224:225]
	v_mul_f32_e32 v207, v93, v93
	v_fmac_f32_e32 v207, v92, v92
	v_mul_f32_e32 v209, v95, v95
	v_fmac_f32_e32 v209, v94, v94
	v_add_f32_e32 v248, v207, v209
	v_mul_f32_e32 v211, v89, v89
	v_mul_f32_e32 v213, v91, v91
	v_fmac_f32_e32 v211, v88, v88
	v_fmac_f32_e32 v213, v90, v90
	v_add_f32_e32 v211, v211, v213
	v_add_f32_e32 v248, v248, v211
	v_mul_f32_e32 v221, v85, v85
	v_mul_f32_e32 v223, v87, v87
	v_fmac_f32_e32 v221, v84, v84
	v_fmac_f32_e32 v223, v86, v86
	v_add_f32_e32 v221, v221, v223
	v_add_f32_e32 v248, v248, v221
	v_mul_f32_e32 v225, v81, v81
	v_mul_f32_e32 v227, v83, v83
	v_fmac_f32_e32 v225, v80, v80
	v_fmac_f32_e32 v227, v82, v82
	v_add_f32_e32 v225, v225, v227
	v_add_f32_e32 v248, v248, v225
	s_mov_b64 s[100:101], 0xa0000
	v_lshl_add_u64 v[172:173], v[170:171], 0, s[100:101]
	global_load_dwordx4 v[206:209], v[172:173], off
	global_load_dwordx4 v[210:213], v[172:173], off offset:64
	global_load_dwordx4 v[220:223], v[172:173], off offset:512
	global_load_dwordx4 v[224:227], v[172:173], off offset:576
	s_waitcnt vmcnt(12)
	v_pk_fma_f32 v[78:79], v[78:79], v[142:143], v[230:231]
	v_pk_fma_f32 v[76:77], v[76:77], v[140:141], v[228:229]
	v_pk_fma_f32 v[74:75], v[74:75], v[138:139], v[234:235]
	v_pk_fma_f32 v[72:73], v[72:73], v[136:137], v[232:233]
	v_pk_fma_f32 v[70:71], v[70:71], v[134:135], v[238:239]
	v_pk_fma_f32 v[68:69], v[68:69], v[132:133], v[236:237]
	v_pk_fma_f32 v[66:67], v[66:67], v[130:131], v[244:245]
	v_pk_fma_f32 v[64:65], v[64:65], v[128:129], v[242:243]
	v_mul_f32_e32 v229, v77, v77
	v_fmac_f32_e32 v229, v76, v76
	v_mul_f32_e32 v231, v79, v79
	v_fmac_f32_e32 v231, v78, v78
	v_add_f32_e32 v249, v229, v231
	v_mul_f32_e32 v233, v73, v73
	v_mul_f32_e32 v235, v75, v75
	v_fmac_f32_e32 v233, v72, v72
	v_fmac_f32_e32 v235, v74, v74
	v_add_f32_e32 v233, v233, v235
	v_add_f32_e32 v249, v249, v233
	v_mul_f32_e32 v237, v69, v69
	v_mul_f32_e32 v239, v71, v71
	v_fmac_f32_e32 v237, v68, v68
	v_fmac_f32_e32 v239, v70, v70
	v_add_f32_e32 v237, v237, v239
	v_add_f32_e32 v249, v249, v237
	v_mul_f32_e32 v243, v65, v65
	v_mul_f32_e32 v245, v67, v67
	v_fmac_f32_e32 v243, v64, v64
	v_fmac_f32_e32 v245, v66, v66
	v_add_f32_e32 v243, v243, v245
	v_add_f32_e32 v249, v249, v243
	s_mov_b64 s[100:101], 0xb0000
	v_lshl_add_u64 v[172:173], v[170:171], 0, s[100:101]
	global_load_dwordx4 v[228:231], v[172:173], off
	global_load_dwordx4 v[232:235], v[172:173], off offset:64
	global_load_dwordx4 v[236:239], v[172:173], off offset:512
	global_load_dwordx4 v[242:245], v[172:173], off offset:576
	s_waitcnt vmcnt(12)
	v_pk_fma_f32 v[62:63], v[62:63], v[142:143], v[146:147]
	v_pk_fma_f32 v[60:61], v[60:61], v[140:141], v[144:145]
	v_pk_fma_f32 v[58:59], v[58:59], v[138:139], v[150:151]
	v_pk_fma_f32 v[56:57], v[56:57], v[136:137], v[148:149]
	v_pk_fma_f32 v[54:55], v[54:55], v[134:135], v[154:155]
	v_pk_fma_f32 v[52:53], v[52:53], v[132:133], v[152:153]
	v_pk_fma_f32 v[46:47], v[46:47], v[130:131], v[158:159]
	v_pk_fma_f32 v[44:45], v[44:45], v[128:129], v[156:157]
	v_mul_f32_e32 v145, v61, v61
	v_fmac_f32_e32 v145, v60, v60
	v_mul_f32_e32 v147, v63, v63
	v_fmac_f32_e32 v147, v62, v62
	v_add_f32_e32 v250, v145, v147
	v_mul_f32_e32 v149, v57, v57
	v_mul_f32_e32 v151, v59, v59
	v_fmac_f32_e32 v149, v56, v56
	v_fmac_f32_e32 v151, v58, v58
	v_add_f32_e32 v149, v149, v151
	v_add_f32_e32 v250, v250, v149
	v_mul_f32_e32 v153, v53, v53
	v_mul_f32_e32 v155, v55, v55
	v_fmac_f32_e32 v153, v52, v52
	v_fmac_f32_e32 v155, v54, v54
	v_add_f32_e32 v153, v153, v155
	v_add_f32_e32 v250, v250, v153
	v_mul_f32_e32 v157, v45, v45
	v_mul_f32_e32 v159, v47, v47
	v_fmac_f32_e32 v157, v44, v44
	v_fmac_f32_e32 v159, v46, v46
	v_add_f32_e32 v157, v157, v159
	v_add_f32_e32 v250, v250, v157
	s_waitcnt vmcnt(8)
	v_pk_fma_f32 v[50:51], v[50:51], v[142:143], v[176:177]
	v_pk_fma_f32 v[48:49], v[48:49], v[140:141], v[174:175]
	v_pk_fma_f32 v[42:43], v[42:43], v[138:139], v[180:181]
	v_pk_fma_f32 v[40:41], v[40:41], v[136:137], v[178:179]
	v_pk_fma_f32 v[38:39], v[38:39], v[134:135], v[184:185]
	v_pk_fma_f32 v[36:37], v[36:37], v[132:133], v[182:183]
	v_pk_fma_f32 v[30:31], v[30:31], v[130:131], v[200:201]
	v_pk_fma_f32 v[28:29], v[28:29], v[128:129], v[198:199]
	v_mul_f32_e32 v175, v49, v49
	v_fmac_f32_e32 v175, v48, v48
	v_mul_f32_e32 v177, v51, v51
	v_fmac_f32_e32 v177, v50, v50
	v_add_f32_e32 v251, v175, v177
	v_mul_f32_e32 v179, v41, v41
	v_mul_f32_e32 v181, v43, v43
	v_fmac_f32_e32 v179, v40, v40
	v_fmac_f32_e32 v181, v42, v42
	v_add_f32_e32 v179, v179, v181
	v_add_f32_e32 v251, v251, v179
	v_mul_f32_e32 v183, v37, v37
	v_mul_f32_e32 v185, v39, v39
	v_fmac_f32_e32 v183, v36, v36
	v_fmac_f32_e32 v185, v38, v38
	v_add_f32_e32 v183, v183, v185
	v_add_f32_e32 v251, v251, v183
	v_mul_f32_e32 v199, v29, v29
	v_mul_f32_e32 v201, v31, v31
	v_fmac_f32_e32 v199, v28, v28
	v_fmac_f32_e32 v201, v30, v30
	v_add_f32_e32 v199, v199, v201
	v_add_f32_e32 v251, v251, v199
	s_waitcnt vmcnt(4)
	v_pk_fma_f32 v[34:35], v[34:35], v[142:143], v[208:209]
	v_pk_fma_f32 v[32:33], v[32:33], v[140:141], v[206:207]
	v_pk_fma_f32 v[26:27], v[26:27], v[138:139], v[212:213]
	v_pk_fma_f32 v[24:25], v[24:25], v[136:137], v[210:211]
	v_pk_fma_f32 v[22:23], v[22:23], v[134:135], v[222:223]
	v_pk_fma_f32 v[20:21], v[20:21], v[132:133], v[220:221]
	v_pk_fma_f32 v[18:19], v[18:19], v[130:131], v[226:227]
	v_pk_fma_f32 v[16:17], v[16:17], v[128:129], v[224:225]
	v_mul_f32_e32 v207, v33, v33
	v_fmac_f32_e32 v207, v32, v32
	v_mul_f32_e32 v209, v35, v35
	v_fmac_f32_e32 v209, v34, v34
	v_add_f32_e32 v252, v207, v209
	v_mul_f32_e32 v211, v25, v25
	v_mul_f32_e32 v213, v27, v27
	v_fmac_f32_e32 v211, v24, v24
	v_fmac_f32_e32 v213, v26, v26
	v_add_f32_e32 v211, v211, v213
	v_add_f32_e32 v252, v252, v211
	v_mul_f32_e32 v221, v21, v21
	v_mul_f32_e32 v223, v23, v23
	v_fmac_f32_e32 v221, v20, v20
	v_fmac_f32_e32 v223, v22, v22
	v_add_f32_e32 v221, v221, v223
	v_add_f32_e32 v252, v252, v221
	v_mul_f32_e32 v225, v17, v17
	v_mul_f32_e32 v227, v19, v19
	v_fmac_f32_e32 v225, v16, v16
	v_fmac_f32_e32 v227, v18, v18
	v_add_f32_e32 v225, v225, v227
	v_add_f32_e32 v252, v252, v225
	s_waitcnt vmcnt(0)
	v_pk_fma_f32 v[14:15], v[14:15], v[142:143], v[230:231]
	v_pk_fma_f32 v[12:13], v[12:13], v[140:141], v[228:229]
	v_pk_fma_f32 v[10:11], v[10:11], v[138:139], v[234:235]
	v_pk_fma_f32 v[8:9], v[8:9], v[136:137], v[232:233]
	v_pk_fma_f32 v[6:7], v[6:7], v[134:135], v[238:239]
	v_pk_fma_f32 v[4:5], v[4:5], v[132:133], v[236:237]
	v_pk_fma_f32 v[2:3], v[2:3], v[130:131], v[244:245]
	v_pk_fma_f32 v[0:1], v[0:1], v[128:129], v[242:243]
	v_mul_f32_e32 v229, v13, v13
	v_fmac_f32_e32 v229, v12, v12
	v_mul_f32_e32 v231, v15, v15
	v_fmac_f32_e32 v231, v14, v14
	v_add_f32_e32 v253, v229, v231
	v_mul_f32_e32 v233, v9, v9
	v_mul_f32_e32 v235, v11, v11
	v_fmac_f32_e32 v233, v8, v8
	v_fmac_f32_e32 v235, v10, v10
	v_add_f32_e32 v233, v233, v235
	v_add_f32_e32 v253, v253, v233
	v_mul_f32_e32 v237, v5, v5
	v_mul_f32_e32 v239, v7, v7
	v_fmac_f32_e32 v237, v4, v4
	v_fmac_f32_e32 v239, v6, v6
	v_add_f32_e32 v237, v237, v239
	v_add_f32_e32 v253, v253, v237
	v_mul_f32_e32 v243, v1, v1
	v_mul_f32_e32 v245, v3, v3
	v_fmac_f32_e32 v243, v0, v0
	v_fmac_f32_e32 v245, v2, v2
	v_add_f32_e32 v243, v243, v245
	v_add_f32_e32 v253, v253, v243
	v_xor_b32_e32 v144, 16, v194
	v_xor_b32_e32 v145, 32, v194
	v_lshlrev_b32_e32 v144, 2, v144
	v_lshlrev_b32_e32 v145, 2, v145
	ds_bpermute_b32 v148, v144, v246
	ds_bpermute_b32 v149, v144, v247
	ds_bpermute_b32 v150, v144, v248
	ds_bpermute_b32 v151, v144, v249
	ds_bpermute_b32 v152, v144, v250
	ds_bpermute_b32 v153, v144, v251
	ds_bpermute_b32 v154, v144, v252
	ds_bpermute_b32 v155, v144, v253
	s_waitcnt lgkmcnt(0)
	v_add_f32_e32 v246, v246, v148
	v_add_f32_e32 v247, v247, v149
	v_add_f32_e32 v248, v248, v150
	v_add_f32_e32 v249, v249, v151
	v_add_f32_e32 v250, v250, v152
	v_add_f32_e32 v251, v251, v153
	v_add_f32_e32 v252, v252, v154
	v_add_f32_e32 v253, v253, v155
	ds_bpermute_b32 v148, v145, v246
	ds_bpermute_b32 v149, v145, v247
	ds_bpermute_b32 v150, v145, v248
	ds_bpermute_b32 v151, v145, v249
	ds_bpermute_b32 v152, v145, v250
	ds_bpermute_b32 v153, v145, v251
	ds_bpermute_b32 v154, v145, v252
	ds_bpermute_b32 v155, v145, v253
	s_waitcnt lgkmcnt(0)
	v_add_f32_e32 v246, v246, v148
	v_add_f32_e32 v247, v247, v149
	v_add_f32_e32 v248, v248, v150
	v_add_f32_e32 v249, v249, v151
	v_add_f32_e32 v250, v250, v152
	v_add_f32_e32 v251, v251, v153
	v_add_f32_e32 v252, v252, v154
	v_add_f32_e32 v253, v253, v155
	s_and_saveexec_b64 s[22:23], s[0:1]
	global_atomic_add_f32 v246, v[168:169], v246, off sc0
	global_atomic_add_f32 v247, v[168:169], v247, off offset:64 sc0
	global_atomic_add_f32 v248, v[168:169], v248, off offset:128 sc0
	global_atomic_add_f32 v249, v[168:169], v249, off offset:192 sc0
	global_atomic_add_f32 v250, v[168:169], v250, off offset:512 sc0
	global_atomic_add_f32 v251, v[168:169], v251, off offset:576 sc0
	global_atomic_add_f32 v252, v[168:169], v252, off offset:640 sc0
	global_atomic_add_f32 v253, v[168:169], v253, off offset:704 sc0
	s_or_b64 exec, exec, s[22:23]
	s_waitcnt vmcnt(0)
	s_branch .LBB0_856

	.amdhsa_kernel _Z11mega_kernel6Params
		.amdhsa_group_segment_fixed_size 0
		.amdhsa_private_segment_fixed_size 0
		.amdhsa_kernarg_size 608
		.amdhsa_user_sgpr_count 2
		.amdhsa_user_sgpr_dispatch_ptr 0
		.amdhsa_user_sgpr_queue_ptr 0
		.amdhsa_user_sgpr_kernarg_segment_ptr 1
		.amdhsa_user_sgpr_dispatch_id 0
		.amdhsa_user_sgpr_kernarg_preload_length 0
		.amdhsa_user_sgpr_kernarg_preload_offset 0
		.amdhsa_user_sgpr_private_segment_size 0
		.amdhsa_uses_dynamic_stack 0
		.amdhsa_enable_private_segment 0
		.amdhsa_system_sgpr_workgroup_id_x 1
		.amdhsa_system_sgpr_workgroup_id_y 0
		.amdhsa_system_sgpr_workgroup_id_z 0
		.amdhsa_system_sgpr_workgroup_info 0
		.amdhsa_system_vgpr_workitem_id 2
		.amdhsa_next_free_vgpr 256
		.amdhsa_next_free_sgpr 102
		.amdhsa_accum_offset 256
		.amdhsa_reserve_vcc 1
		.amdhsa_float_round_mode_32 0
		.amdhsa_float_round_mode_16_64 0
		.amdhsa_float_denorm_mode_32 3
		.amdhsa_float_denorm_mode_16_64 3
		.amdhsa_dx10_clamp 1
		.amdhsa_ieee_mode 1
		.amdhsa_fp16_overflow 0
		.amdhsa_tg_split 0
		.amdhsa_exception_fp_ieee_invalid_op 0
		.amdhsa_exception_fp_denorm_src 0
		.amdhsa_exception_fp_ieee_div_zero 0
		.amdhsa_exception_fp_ieee_overflow 0
		.amdhsa_exception_fp_ieee_underflow 0
		.amdhsa_exception_fp_ieee_inexact 0
		.amdhsa_exception_int_div_zero 0
	.end_amdhsa_kernel

amdhsa.kernels:
  - .agpr_count:     0
    .args:
      - .offset:         0
        .size:           352
        .value_kind:     by_value
      - .offset:         352
        .size:           4
        .value_kind:     hidden_block_count_x
      - .offset:         356
        .size:           4
        .value_kind:     hidden_block_count_y
      - .offset:         360
        .size:           4
        .value_kind:     hidden_block_count_z
      - .offset:         364
        .size:           2
        .value_kind:     hidden_group_size_x
      - .offset:         366
        .size:           2
        .value_kind:     hidden_group_size_y
      - .offset:         368
        .size:           2
        .value_kind:     hidden_group_size_z
      - .offset:         370
        .size:           2
        .value_kind:     hidden_remainder_x
      - .offset:         372
        .size:           2
        .value_kind:     hidden_remainder_y
      - .offset:         374
        .size:           2
        .value_kind:     hidden_remainder_z
      - .offset:         392
        .size:           8
        .value_kind:     hidden_global_offset_x
      - .offset:         400
        .size:           8
        .value_kind:     hidden_global_offset_y
      - .offset:         408
        .size:           8
        .value_kind:     hidden_global_offset_z
      - .offset:         416
        .size:           2
        .value_kind:     hidden_grid_dims
      - .offset:         440
        .size:           8
        .value_kind:     hidden_multigrid_sync_arg
      - .offset:         472
        .size:           4
        .value_kind:     hidden_dynamic_lds_size
    .group_segment_fixed_size: 0
    .kernarg_segment_align: 8
    .kernarg_segment_size: 608
    .language:       OpenCL C
    .language_version:
      - 2
      - 0
    .max_flat_workgroup_size: 512
    .name:           _Z11mega_kernel6Params
    .private_segment_fixed_size: 0
    .sgpr_count:     108
    .sgpr_spill_count: 113
    .symbol:         _Z11mega_kernel6Params.kd
    .uniform_work_group_size: 1
    .uses_dynamic_stack: false
    .vgpr_count:     256
    .vgpr_spill_count: 0
    .wavefront_size: 64
